# MLA loop: K/V tile pointers kept as absolute addresses (9 fewer address instructions per tile per wave)
# speedup vs baseline: 1.0112x; 1.0001x over previous
; DI int TID() { int t = threadIdx.x; asm volatile("" : "+v"(t)); return t; }
; template <int DQK, int NM>
; DI void attn_item(const bf16_t* Qb, const bf16_t* Kb, size_t mstride, const bf16_t* VTb,
;                   int q0, int nkt, float cs, bf16_t* Orow  , float lam, float outscale, const float* subw, char* smem) {
;     ...
;   const int tid = TID(), lane = tid & 63, wv = tid >> 6, l31 = lane & 31, hh = lane >> 5;
;   const int m = wv / WPM, wq = wv % WPM;
;   const int qp = q0 + wq * 32 + l31;
;   bf16x8 qf[NS];
;   {
;     const bf16_t* qptr = Qb + m * mstride + (size_t)qp * DQK + hh * 8;
; #pragma unroll
;     for (int s = 0; s < NS; ++s) qf[s] = *(const bf16x8*)(qptr + s * 16);
;   }
;   f32x16 oacc[4];
; #pragma unroll
;   for (int db = 0; db < 4; ++db)
; #pragma unroll
;     for (int i = 0; i < 16; ++i) oacc[db][i] = 0.f;
;   float mrun = -1e30f, lrun = 0.f;
;   uint4 kreg0, kreg1, kreg2, vreg0, vreg1;
;   kreg2 = make_uint4(0, 0, 0, 0);
;   int kgo[3], klo[3];
; #pragma unroll
;   for (int j = 0; j < 3; ++j) {
;     int c = tid + NTHR * j, mm = c / (64 * KCH), rem = c - mm * (64 * KCH), row = rem / KCH, kc = rem - row * KCH;
;     kgo[j] = row * DQK + kc * 8; klo[j] = (mm * 64 + row) * KSTR + kc * 16;
;     if (NM == 2) kgo[j] += mm * (int)mstride;
;   }
;   const int vgo0 = (tid >> 3) * PL + (tid & 7) * 8, vgo1 = ((tid + NTHR) >> 3) * PL + (tid & 7) * 8;
;   const int vlo0 = KT_BYTES + (tid >> 3) * VSTR + (tid & 7) * 16, vlo1 = KT_BYTES + ((tid + NTHR) >> 3) * VSTR + (tid & 7) * 16;
; DI void phase_attn_mla(const Params& p, bool do_ctx, char* smem) {
;     ...
;   for (int q = slot; q < 4 * 32; q += nslots) {
;     int bh = (q >> 5) * 8 + xcd, qb = (q & 31) + 1;
;     int b = bh >> 3, h = bh & 7;
;     attn_item<192, 1>(Q + (size_t)bh * PL * 192, K + (size_t)bh * PL * 192, 0, VT + (size_t)bh * 128 * PL, qb * 256, PL / 64, cs,
.LBB0_125:
	s_ashr_i32 s0, s3, 2
	s_and_b32 s0, s0, -8
	s_or_b32 s24, s0, s30
	s_mul_i32 s27, s24, 0x318000
	s_mul_hi_i32 s25, s24, 0x318000
	s_add_u32 s40, s52, s27
	s_addc_u32 s41, s53, s25
	v_readlane_b32 s0, v252, 10
	v_readlane_b32 s1, v252, 11
	s_add_u32 s0, s0, s27
	s_waitcnt vmcnt(1)
	v_mov_b32_e32 v2, v167
	s_addc_u32 s1, s1, s25
	s_mul_i32 s39, s24, 0x210000
	v_readlane_b32 s28, v252, 12
	s_mul_hi_i32 s38, s24, 0x210000
	v_ashrrev_i32_e32 v0, 6, v2
	v_readlane_b32 s29, v252, 13
	s_add_u32 s28, s28, s39
	v_lshrrev_b32_e32 v1, 29, v0
	s_addc_u32 s29, s29, s38
	s_lshl_b32 s37, s3, 8
	v_add_u32_e32 v1, v0, v1
	s_and_b32 s37, s37, 0x1f00
	v_ashrrev_i32_e32 v20, 3, v1
	s_addk_i32 s37, 0x100
	v_and_b32_e32 v9, 31, v2
	v_mul_i32_i24_e32 v1, 8, v20
	v_sub_u32_e32 v0, v0, v1
	v_or_b32_e32 v1, s37, v9
	v_bfe_u32 v3, v2, 5, 1
	v_lshl_add_u32 v140, v0, 5, v1
	v_mov_b64_e32 v[0:1], s[40:41]
	s_movk_i32 s34, 0x180
	v_mad_u64_u32 v[0:1], s[40:41], v140, s34, v[0:1]
	v_lshlrev_b32_e32 v170, 4, v3
	v_mov_b32_e32 v171, v141
	v_lshl_add_u64 v[0:1], v[0:1], 0, v[170:171]
	s_mov_b32 s35, 0x2aaaaaab
	global_load_dwordx4 v[142:145], v[0:1], off
	global_load_dwordx4 v[136:139], v[0:1], off offset:32
	global_load_dwordx4 v[132:135], v[0:1], off offset:64
	global_load_dwordx4 v[128:131], v[0:1], off offset:96
	global_load_dwordx4 v[124:127], v[0:1], off offset:128
	global_load_dwordx4 v[120:123], v[0:1], off offset:160
	global_load_dwordx4 v[116:119], v[0:1], off offset:192
	global_load_dwordx4 v[112:115], v[0:1], off offset:224
	global_load_dwordx4 v[108:111], v[0:1], off offset:256
	global_load_dwordx4 v[104:107], v[0:1], off offset:288
	global_load_dwordx4 v[100:103], v[0:1], off offset:320
	global_load_dwordx4 v[96:99], v[0:1], off offset:352
	v_mul_hi_i32 v0, v2, s35
	v_lshrrev_b32_e32 v1, 31, v0
	v_ashrrev_i32_e32 v0, 8, v0
	v_lshlrev_b32_e32 v168, 3, v3
	v_add_u32_e32 v3, v0, v1
	s_movk_i32 s37, 0xfa00
	v_mad_i32_i24 v0, v3, s37, v2
	v_mul_hi_i32 v1, v0, s35
	v_lshrrev_b32_e32 v4, 31, v1
	v_ashrrev_i32_e32 v1, 2, v1
	v_add_u32_e32 v4, v1, v4
	s_movk_i32 s42, 0xffe8
	v_mad_u64_u32 v[0:1], s[40:41], v4, s42, v[0:1]
	s_movk_i32 s34, 0xc0
	v_mul_lo_u32 v1, v4, s34
	v_lshl_add_u32 v172, v0, 3, v1
	v_lshl_add_u32 v1, v3, 6, v4
	s_movk_i32 s43, 0x190
	v_mul_lo_u32 v1, v1, s43
	v_add_u32_e32 v3, 0x200, v2
	v_lshl_add_u32 v197, v0, 4, v1
	v_mul_hi_i32 v0, v3, s35
	v_lshrrev_b32_e32 v1, 31, v0
	v_ashrrev_i32_e32 v0, 8, v0
	v_add_u32_e32 v4, v0, v1
	v_mad_i32_i24 v0, v4, s37, v3
	v_mul_hi_i32 v1, v0, s35
	v_lshrrev_b32_e32 v5, 31, v1
	v_ashrrev_i32_e32 v1, 2, v1
	v_add_u32_e32 v5, v1, v5
	v_mad_u64_u32 v[0:1], s[40:41], v5, s42, v[0:1]
	v_mul_lo_u32 v1, v5, s34
	v_lshl_add_u32 v174, v0, 3, v1
	v_lshl_add_u32 v1, v4, 6, v5
	v_mul_lo_u32 v1, v1, s43
	v_lshl_add_u32 v215, v0, 4, v1
	v_add_u32_e32 v0, 0x400, v2
	v_mul_hi_i32 v1, v0, s35
	v_lshrrev_b32_e32 v4, 31, v1
	v_ashrrev_i32_e32 v1, 8, v1
	v_add_u32_e32 v4, v1, v4
	v_mad_i32_i24 v0, v4, s37, v0
	v_mul_hi_i32 v1, v0, s35
	v_lshrrev_b32_e32 v5, 31, v1
	v_ashrrev_i32_e32 v1, 2, v1
	v_add_u32_e32 v5, v1, v5
	v_mad_u64_u32 v[0:1], s[40:41], v5, s42, v[0:1]
	v_mul_lo_u32 v1, v5, s34
	v_lshl_add_u32 v176, v0, 3, v1
	v_lshl_add_u32 v1, v4, 6, v5
	v_mul_lo_u32 v1, v1, s43
	v_lshl_add_u32 v216, v0, 4, v1
	v_ashrrev_i32_e32 v21, 3, v2
	s_movk_i32 s34, 0x2100
	v_and_b32_e32 v1, 7, v2
	v_mul_lo_u32 v0, v21, s34
	v_lshlrev_b32_e32 v2, 3, v1
	v_ashrrev_i32_e32 v32, 3, v3
	v_ashrrev_i32_e32 v173, 31, v172
	s_waitcnt vmcnt(16)
; #define GLOAD(kt_) do { const bf16_t* kp_ = Kb + (size_t)(kt_) * 64 * DQK; const bf16_t* vp_ = VTb + (kt_) * 64; \
;     kreg0 = *(const uint4*)(kp_ + kgo[0]); kreg1 = *(const uint4*)(kp_ + kgo[1]); if (NKC > 2) kreg2 = *(const uint4*)(kp_ + kgo[2]); \
;     vreg0 = *(const uint4*)(vp_ + vgo0); vreg1 = *(const uint4*)(vp_ + vgo1); } while (0)
; #define SSTORE(buf_) do { char* b_ = (buf_); \
;     *(uint4*)(b_ + klo[0]) = kreg0; *(uint4*)(b_ + klo[1]) = kreg1; if (NKC > 2) *(uint4*)(b_ + klo[2]) = kreg2; \
;     *(uint4*)(b_ + vlo0) = vreg0; *(uint4*)(b_ + vlo1) = vreg1; } while (0)
; template <int DQK, int NM>
; DI void attn_item(const bf16_t* Qb, const bf16_t* Kb, size_t mstride, const bf16_t* VTb,
;                   int q0, int nkt, float cs, bf16_t* Orow  , float lam, float outscale, const float* subw, char* smem) {
;     ...
;   f32x16 oacc[4];
; #pragma unroll
;   for (int db = 0; db < 4; ++db)
; #pragma unroll
;     for (int i = 0; i < 16; ++i) oacc[db][i] = 0.f;
;   float mrun = -1e30f, lrun = 0.f;
;   uint4 kreg0, kreg1, kreg2, vreg0, vreg1;
;   kreg2 = make_uint4(0, 0, 0, 0);
;   int kgo[3], klo[3];
; #pragma unroll
;   for (int j = 0; j < 3; ++j) {
;     int c = tid + NTHR * j, mm = c / (64 * KCH), rem = c - mm * (64 * KCH), row = rem / KCH, kc = rem - row * KCH;
;     kgo[j] = row * DQK + kc * 8; klo[j] = (mm * 64 + row) * KSTR + kc * 16;
;     if (NM == 2) kgo[j] += mm * (int)mstride;
;   }
;   const int vgo0 = (tid >> 3) * PL + (tid & 7) * 8, vgo1 = ((tid + NTHR) >> 3) * PL + (tid & 7) * 8;
;   const int vlo0 = KT_BYTES + (tid >> 3) * VSTR + (tid & 7) * 16, vlo1 = KT_BYTES + ((tid + NTHR) >> 3) * VSTR + (tid & 7) * 16;
;     ...
;   GLOAD(0); SSTORE(smem); __syncthreads();
	v_or_b32_e32 v178, v0, v2
	v_mul_lo_u32 v0, v32, s34
	v_lshlrev_b64 v[10:11], 1, v[172:173]
	v_or_b32_e32 v180, v0, v2
	v_lshlrev_b32_e32 v8, 4, v1
	v_lshl_add_u64 v[0:1], s[0:1], 0, v[10:11]
	global_load_dwordx4 v[22:25], v[0:1], off
	v_ashrrev_i32_e32 v181, 31, v180
	v_ashrrev_i32_e32 v175, 31, v174
	v_ashrrev_i32_e32 v177, 31, v176
	v_lshlrev_b64 v[18:19], 1, v[180:181]
	v_lshlrev_b64 v[12:13], 1, v[174:175]
	v_lshlrev_b64 v[14:15], 1, v[176:177]
	v_ashrrev_i32_e32 v179, 31, v178
	v_lshl_add_u64 v[4:5], s[28:29], 0, v[18:19]
	v_lshl_add_u64 v[30:31], s[0:1], 0, v[14:15]
	v_lshlrev_b64 v[16:17], 1, v[178:179]
	global_load_dwordx4 v[4:7], v[4:5], off
	v_lshl_add_u64 v[0:1], s[0:1], 0, v[12:13]
	v_add_u32_e32 v171, 0, v197
	global_load_dwordx4 v[26:29], v[0:1], off
	s_movk_i32 s34, 0x90
	v_mad_u64_u32 v[182:183], s[40:41], v21, s34, v[8:9]
	v_mad_u64_u32 v[184:185], s[40:41], v32, s34, v[8:9]
	s_add_u32 s40, s39, 0x12d00080
	v_add_u32_e32 v169, 0, v215
	v_add_u32_e32 v198, 0, v216
	v_add_u32_e32 v199, 0, v182
	s_addc_u32 s41, s38, 0
	s_add_u32 s38, s27, 0xca06000
	v_add_u32_e32 v183, 0, v184
	s_addc_u32 s39, s25, 0
	v_mov_b32_e32 v32, v141
	v_mov_b32_e32 v33, v141
	v_mov_b32_e32 v46, v141
	v_mov_b32_e32 v47, v141
	v_mul_u32_u24_e32 v214, 0x90, v9
	v_lshl_add_u64 v[186:187], s[40:41], 0, v[16:17]
	v_lshl_add_u64 v[188:189], s[40:41], 0, v[18:19]
	v_lshl_add_u64 v[190:191], s[38:39], 0, v[10:11]
	v_lshl_add_u64 v[192:193], s[38:39], 0, v[12:13]
	v_mov_b32_e32 v34, v141
	v_mov_b32_e32 v35, v141
	v_mov_b32_e32 v36, v141
	v_mov_b32_e32 v37, v141
	v_mov_b32_e32 v38, v141
	v_mov_b32_e32 v39, v141
	v_mov_b32_e32 v40, v141
	v_mov_b32_e32 v41, v141
	v_mov_b32_e32 v42, v141
	v_mov_b32_e32 v43, v141
	v_mov_b32_e32 v44, v141
	v_mov_b32_e32 v45, v141
	v_mov_b64_e32 v[62:63], v[46:47]
	s_mov_b32 s37, 1
	s_movk_i32 s27, 0x2000
	v_mov_b32_e32 v218, 0xf149f2ca
	v_mov_b32_e32 v185, 0
	v_mov_b64_e32 v[60:61], v[44:45]
	v_mov_b64_e32 v[58:59], v[42:43]
	v_mov_b64_e32 v[56:57], v[40:41]
	v_mov_b64_e32 v[54:55], v[38:39]
	v_mov_b64_e32 v[52:53], v[36:37]
	v_mov_b64_e32 v[50:51], v[34:35]
	v_mov_b64_e32 v[48:49], v[32:33]
	s_waitcnt vmcnt(2)
	ds_write_b128 v171, v[22:25]
	global_load_dwordx4 v[22:25], v[30:31], off
	v_lshl_add_u64 v[0:1], s[28:29], 0, v[16:17]
	global_load_dwordx4 v[0:3], v[0:1], off
	s_waitcnt vmcnt(2)
	ds_write_b128 v169, v[26:29]
	s_waitcnt vmcnt(1)
	ds_write_b128 v198, v[22:25]
	s_waitcnt vmcnt(0)
	ds_write_b128 v199, v[0:3] offset:25600
	v_lshl_or_b32 v0, v20, 6, v9
	v_mul_lo_u32 v217, v0, s43
	v_mov_b32_e32 v0, 0x318000
	ds_write_b128 v183, v[4:7] offset:25600
	v_mad_i64_i32 v[194:195], s[24:25], s24, v0, v[14:15]
	v_lshl_add_u64 v[186:187], v[186:187], 0, s[20:21]
	v_lshl_add_u64 v[188:189], v[188:189], 0, s[20:21]
	v_lshl_add_u64 v[190:191], v[190:191], 0, s[20:21]
	v_lshl_add_u64 v[192:193], v[192:193], 0, s[20:21]
	s_mov_b64 s[34:35], 0xca06000
	v_lshl_add_u64 v[194:195], v[194:195], 0, s[20:21]
	v_lshl_add_u64 v[194:195], v[194:195], 0, s[34:35]
	v_mov_b64_e32 v[16:17], v[32:33]
	v_mov_b64_e32 v[0:1], v[32:33]
	v_mov_b64_e32 v[18:19], v[34:35]
	v_mov_b64_e32 v[20:21], v[36:37]
	v_mov_b64_e32 v[22:23], v[38:39]
	v_mov_b64_e32 v[24:25], v[40:41]
	v_mov_b64_e32 v[26:27], v[42:43]
	v_mov_b64_e32 v[28:29], v[44:45]
	v_mov_b64_e32 v[30:31], v[46:47]
	v_mov_b64_e32 v[2:3], v[34:35]
	v_mov_b64_e32 v[4:5], v[36:37]
	v_mov_b64_e32 v[6:7], v[38:39]
	v_mov_b64_e32 v[8:9], v[40:41]
	v_mov_b64_e32 v[10:11], v[42:43]
	v_mov_b64_e32 v[12:13], v[44:45]
	v_mov_b64_e32 v[14:15], v[46:47]
	s_waitcnt lgkmcnt(0)
	s_barrier
	s_branch .LBB0_127

; #define PIN() do { asm volatile("" ::: "memory"); __builtin_amdgcn_sched_barrier(0); } while (0)
; #define GLOAD(kt_) do { const bf16_t* kp_ = Kb + (size_t)(kt_) * 64 * DQK; const bf16_t* vp_ = VTb + (kt_) * 64; \
;     kreg0 = *(const uint4*)(kp_ + kgo[0]); kreg1 = *(const uint4*)(kp_ + kgo[1]); if (NKC > 2) kreg2 = *(const uint4*)(kp_ + kgo[2]); \
;     vreg0 = *(const uint4*)(vp_ + vgo0); vreg1 = *(const uint4*)(vp_ + vgo1); } while (0)
; #define KLD(dst_, s_) do { dst_[0] = *(const bf16x8*)(kbase + (s_) * 32); dst_[1] = *(const bf16x8*)(kbase + 32 * KSTR + (s_) * 32); \
;         dst_[2] = *(const bf16x8*)(kbase + ((s_) + 1) * 32); dst_[3] = *(const bf16x8*)(kbase + 32 * KSTR + ((s_) + 1) * 32); } while (0)
; template <int DQK, int NM>
; DI void attn_item(const bf16_t* Qb, const bf16_t* Kb, size_t mstride, const bf16_t* VTb,
;                   int q0, int nkt, float cs, bf16_t* Orow  , float lam, float outscale, const float* subw, char* smem) {
;     ...
;   for (int kt = 0; kt < nkt; ++kt) {
;     const char* cur = smem + (kt & 1) * BUF;
;     GLOAD(kt + 1 < nkt ? kt + 1 : kt);
;     PIN();
;     f32x16 sacc[2];
; #pragma unroll
;     for (int kb = 0; kb < 2; ++kb)
; #pragma unroll
;       for (int i = 0; i < 16; ++i) sacc[kb][i] = 0.f;
;     const char* kbase = cur + (m * 64 + l31) * KSTR + hh * 16;
;     {
;       bf16x8 kfa[4], kfb[4];
;     ...
;       KLD(kfa, 0);
; #pragma unroll
;       for (int g = 0; g < NS / 2; ++g) {
;         PIN();
;         if (g + 1 < NS / 2) { if (g & 1) KLD(kfa, 2 * g + 2); else KLD(kfb, 2 * g + 2); }
;         PIN();
;         if (g & 1) KMM(kfb, 2 * g); else KMM(kfa, 2 * g);
;       }
;     ...
;     }
;     float mx = sacc[0][0];
; #pragma unroll
;     for (int i = 1; i < 16; ++i) mx = fmaxf(mx, sacc[0][i]);
; #pragma unroll
;     for (int i = 0; i < 16; ++i) mx = fmaxf(mx, sacc[1][i]);
;     {
;       const auto rr = __builtin_amdgcn_permlane32_swap(__float_as_uint(mx), __float_as_uint(mx), false, false);
;       mx = fmaxf(__uint_as_float(rr[0]), __uint_as_float(rr[1]));
;     }
;     if (__any((mx - mrun) * cs > 8.f)) {
;       const float mnew = fmaxf(mrun, mx);
;       const float alpha = __builtin_amdgcn_exp2f((mrun - mnew) * cs);
;       mrun = mnew;
;       lrun *= alpha;
; #pragma unroll
;       for (int db = 0; db < 4; ++db)
; #pragma unroll
;         for (int i = 0; i < 16; ++i) oacc[db][i] *= alpha;
;     }
.LBB0_127:
	global_load_dwordx4 v[158:161], v[190:191], off
	global_load_dwordx4 v[154:157], v[192:193], off
	global_load_dwordx4 v[162:165], v[194:195], off
	global_load_dwordx4 v[150:153], v[186:187], off
	global_load_dwordx4 v[146:149], v[188:189], off
	s_and_b32 s24, 1, s37
	s_cselect_b32 s25, 0, 0xac00
	s_add_i32 s25, s25, 0
	v_add3_u32 v196, s25, v217, v170
	ds_read_b128 v[64:67], v196
	ds_read_b128 v[220:223], v196 offset:32
	ds_read_b128 v[68:71], v196 offset:12800
	ds_read_b128 v[224:227], v196 offset:12832
	ds_read_b128 v[228:231], v196 offset:64
	ds_read_b128 v[232:235], v196 offset:96
	ds_read_b128 v[236:239], v196 offset:12864
	ds_read_b128 v[240:243], v196 offset:12896
	s_waitcnt lgkmcnt(7)
	v_mfma_f32_32x32x16_bf16 v[80:95], v[64:67], v[142:145], 0
	s_waitcnt lgkmcnt(5)
	v_mfma_f32_32x32x16_bf16 v[64:79], v[68:71], v[142:145], 0
	v_mfma_f32_32x32x16_bf16 v[80:95], v[220:223], v[136:139], v[80:95]
	s_waitcnt lgkmcnt(4)
	v_mfma_f32_32x32x16_bf16 v[64:79], v[224:227], v[136:139], v[64:79]
	ds_read_b128 v[220:223], v196 offset:128
	ds_read_b128 v[224:227], v196 offset:160
	ds_read_b128 v[244:247], v196 offset:12928
	ds_read_b128 v[248:251], v196 offset:12960
	s_waitcnt lgkmcnt(7)
	v_mfma_f32_32x32x16_bf16 v[80:95], v[228:231], v[132:135], v[80:95]
	s_waitcnt lgkmcnt(5)
	v_mfma_f32_32x32x16_bf16 v[64:79], v[236:239], v[132:135], v[64:79]
	v_mfma_f32_32x32x16_bf16 v[80:95], v[232:235], v[128:131], v[80:95]
	s_waitcnt lgkmcnt(4)
	v_mfma_f32_32x32x16_bf16 v[64:79], v[240:243], v[128:131], v[64:79]
	ds_read_b128 v[228:231], v196 offset:192
	ds_read_b128 v[232:235], v196 offset:224
	ds_read_b128 v[236:239], v196 offset:12992
	ds_read_b128 v[240:243], v196 offset:13024
	s_waitcnt lgkmcnt(7)
	v_mfma_f32_32x32x16_bf16 v[80:95], v[220:223], v[124:127], v[80:95]
	s_waitcnt lgkmcnt(5)
	v_mfma_f32_32x32x16_bf16 v[64:79], v[244:247], v[124:127], v[64:79]
	v_mfma_f32_32x32x16_bf16 v[80:95], v[224:227], v[120:123], v[80:95]
	s_waitcnt lgkmcnt(4)
	v_mfma_f32_32x32x16_bf16 v[64:79], v[248:251], v[120:123], v[64:79]
	ds_read_b128 v[220:223], v196 offset:256
	ds_read_b128 v[224:227], v196 offset:288
	ds_read_b128 v[244:247], v196 offset:13056
	ds_read_b128 v[248:251], v196 offset:13088
	s_waitcnt lgkmcnt(7)
	v_mfma_f32_32x32x16_bf16 v[80:95], v[228:231], v[116:119], v[80:95]
	s_waitcnt lgkmcnt(5)
	v_mfma_f32_32x32x16_bf16 v[64:79], v[236:239], v[116:119], v[64:79]
	v_mfma_f32_32x32x16_bf16 v[80:95], v[232:235], v[112:115], v[80:95]
	s_waitcnt lgkmcnt(4)
	v_mfma_f32_32x32x16_bf16 v[64:79], v[240:243], v[112:115], v[64:79]
	ds_read_b128 v[228:231], v196 offset:320
	ds_read_b128 v[232:235], v196 offset:352
	ds_read_b128 v[236:239], v196 offset:13120
	ds_read_b128 v[240:243], v196 offset:13152
	s_waitcnt lgkmcnt(7)
	v_mfma_f32_32x32x16_bf16 v[80:95], v[220:223], v[108:111], v[80:95]
	s_waitcnt lgkmcnt(5)
	v_mfma_f32_32x32x16_bf16 v[64:79], v[244:247], v[108:111], v[64:79]
	v_mfma_f32_32x32x16_bf16 v[80:95], v[224:227], v[104:107], v[80:95]
	s_waitcnt lgkmcnt(4)
	v_mfma_f32_32x32x16_bf16 v[64:79], v[248:251], v[104:107], v[64:79]
	s_waitcnt lgkmcnt(3)
	v_mfma_f32_32x32x16_bf16 v[80:95], v[228:231], v[100:103], v[80:95]
	s_waitcnt lgkmcnt(2)
	v_mfma_f32_32x32x16_bf16 v[80:95], v[232:235], v[96:99], v[80:95]
	s_waitcnt lgkmcnt(1)
	v_mfma_f32_32x32x16_bf16 v[64:79], v[236:239], v[100:103], v[64:79]
	s_mov_b64 s[34:35], 0x80
	s_add_i32 s37, s37, 1
	v_lshl_add_u64 v[186:187], v[186:187], 0, s[34:35]
	v_lshl_add_u64 v[188:189], v[188:189], 0, s[34:35]
	s_mov_b64 s[34:35], 0x6000
	v_lshl_add_u64 v[190:191], v[190:191], 0, s[34:35]
	v_lshl_add_u64 v[192:193], v[192:193], 0, s[34:35]
	v_lshl_add_u64 v[194:195], v[194:195], 0, s[34:35]
	s_nop 1
	v_max_f32_e32 v196, v80, v81
	v_max3_f32 v196, v196, v82, v83
	v_max3_f32 v196, v196, v84, v85
	v_max3_f32 v196, v196, v86, v87
	v_max3_f32 v196, v196, v88, v89
	s_waitcnt lgkmcnt(0)
	v_mfma_f32_32x32x16_bf16 v[64:79], v[240:243], v[96:99], v[64:79]
	v_max3_f32 v196, v196, v90, v91
	v_max3_f32 v196, v196, v92, v93
	v_max3_f32 v196, v196, v94, v95
	s_cmp_eq_u32 s24, 1
	s_cselect_b32 s24, 0xac00, 0
	v_add_u32_e32 v206, s24, v197
	v_add_u32_e32 v211, s24, v216
	s_nop 4
	v_max3_f32 v196, v196, v64, v65
	v_max3_f32 v196, v196, v66, v67
	v_max3_f32 v196, v196, v68, v69
	v_max3_f32 v196, v196, v70, v71
	v_max3_f32 v196, v196, v72, v73
	v_max3_f32 v196, v196, v74, v75
	v_max3_f32 v196, v196, v76, v77
	v_max3_f32 v196, v196, v78, v79
	v_mov_b32_e32 v219, v196
	s_nop 1
	v_permlane32_swap_b32_e32 v196, v219
	v_max_f32_e32 v196, v196, v219
	v_sub_f32_e32 v219, v196, v218
	v_mul_f32_e32 v219, 0x3dd53b95, v219
	v_cmp_lt_f32_e32 vcc, s5, v219
	s_cbranch_vccz .LBB0_126
	v_max_f32_e32 v196, v196, v196
	v_max_f32_e32 v219, v218, v218
	v_max_f32_e32 v219, v219, v196
	v_sub_f32_e32 v196, v218, v219
	v_mul_f32_e32 v196, 0x3dd53b95, v196
	v_exp_f32_e32 v196, v196
	v_mov_b32_e32 v218, v219
	v_pk_mul_f32 v[46:47], v[46:47], v[196:197] op_sel_hi:[1,0]
	v_pk_mul_f32 v[44:45], v[44:45], v[196:197] op_sel_hi:[1,0]
	v_pk_mul_f32 v[42:43], v[42:43], v[196:197] op_sel_hi:[1,0]
	v_pk_mul_f32 v[40:41], v[40:41], v[196:197] op_sel_hi:[1,0]
	v_pk_mul_f32 v[38:39], v[38:39], v[196:197] op_sel_hi:[1,0]
	v_pk_mul_f32 v[36:37], v[36:37], v[196:197] op_sel_hi:[1,0]
	v_pk_mul_f32 v[34:35], v[34:35], v[196:197] op_sel_hi:[1,0]
	v_pk_mul_f32 v[32:33], v[32:33], v[196:197] op_sel_hi:[1,0]
	v_pk_mul_f32 v[62:63], v[62:63], v[196:197] op_sel_hi:[1,0]
	v_pk_mul_f32 v[60:61], v[60:61], v[196:197] op_sel_hi:[1,0]
	v_pk_mul_f32 v[58:59], v[58:59], v[196:197] op_sel_hi:[1,0]
	v_pk_mul_f32 v[56:57], v[56:57], v[196:197] op_sel_hi:[1,0]
	v_pk_mul_f32 v[54:55], v[54:55], v[196:197] op_sel_hi:[1,0]
	v_pk_mul_f32 v[52:53], v[52:53], v[196:197] op_sel_hi:[1,0]
	v_pk_mul_f32 v[50:51], v[50:51], v[196:197] op_sel_hi:[1,0]
	v_pk_mul_f32 v[48:49], v[48:49], v[196:197] op_sel_hi:[1,0]
	v_pk_mul_f32 v[30:31], v[30:31], v[196:197] op_sel_hi:[1,0]
	v_pk_mul_f32 v[28:29], v[28:29], v[196:197] op_sel_hi:[1,0]
	v_pk_mul_f32 v[26:27], v[26:27], v[196:197] op_sel_hi:[1,0]
	v_pk_mul_f32 v[24:25], v[24:25], v[196:197] op_sel_hi:[1,0]
	v_pk_mul_f32 v[22:23], v[22:23], v[196:197] op_sel_hi:[1,0]
	v_pk_mul_f32 v[20:21], v[20:21], v[196:197] op_sel_hi:[1,0]
	v_pk_mul_f32 v[18:19], v[18:19], v[196:197] op_sel_hi:[1,0]
	v_pk_mul_f32 v[16:17], v[16:17], v[196:197] op_sel_hi:[1,0]
	v_pk_mul_f32 v[14:15], v[14:15], v[196:197] op_sel_hi:[1,0]
	v_pk_mul_f32 v[12:13], v[12:13], v[196:197] op_sel_hi:[1,0]
	v_pk_mul_f32 v[10:11], v[10:11], v[196:197] op_sel_hi:[1,0]
	v_pk_mul_f32 v[8:9], v[8:9], v[196:197] op_sel_hi:[1,0]
	v_pk_mul_f32 v[6:7], v[6:7], v[196:197] op_sel_hi:[1,0]
	v_pk_mul_f32 v[4:5], v[4:5], v[196:197] op_sel_hi:[1,0]
	v_pk_mul_f32 v[2:3], v[2:3], v[196:197] op_sel_hi:[1,0]
	v_pk_mul_f32 v[0:1], v[0:1], v[196:197] op_sel_hi:[1,0]
	v_mul_f32_e32 v185, v185, v196
	s_branch .LBB0_126
